# attention inner loop: all 12 K-fragment ds_reads issued up front with counted lgkmcnt, V-fragment reads issued before softmax (into P3-unused VGPRs v210-249)
# speedup vs baseline: 1.0092x; 1.0092x over previous
; DI u32x2 pack4(f32x4 v) { return u32x2{pack2(v[0], v[1]), pack2(v[2], v[3])}; }
; DI float xmax16(float x) { u32x2 r = __builtin_amdgcn_permlane16_swap(__float_as_uint(x), __float_as_uint(x), false, false); return fmaxf(__uint_as_float(r.x), __uint_as_float(r.y)); }
; DI float xmax32(float x) { u32x2 r = __builtin_amdgcn_permlane32_swap(__float_as_uint(x), __float_as_uint(x), false, false); return fmaxf(__uint_as_float(r.x), __uint_as_float(r.y)); }
; DI void attn_item(const int tid_, const Params& p, int l, int item, char* s0, char* s1, char* s2) {
;     ...
;       bf16x8 pf[2][2];
; #pragma unroll
;       for (int nt = 0; nt < 2; ++nt) {
;         float mx = -1e30f;
; #pragma unroll
;         for (int mt = 0; mt < 4; ++mt)
; #pragma unroll
;           for (int e = 0; e < 4; ++e) mx = fmaxf(mx, s[mt][nt][e]);
;         mx = xmax16(mx);
;         mx = xmax32(mx);
;         const float mnew = fmaxf(mrow[nt], mx);
;         const float alpha = __builtin_amdgcn_exp2f(mrow[nt] - mnew);
;         mrow[nt] = mnew;
;         float ps = 0.f;
; #pragma unroll
;         for (int mt = 0; mt < 4; ++mt)
; #pragma unroll
;           for (int e = 0; e < 4; ++e) {
;             float pv = __builtin_amdgcn_exp2f(s[mt][nt][e] - mnew);
;             s[mt][nt][e] = pv;
;             ps += pv;
;           }
;         lsum[nt] = lsum[nt] * alpha + ps;
;         if (__builtin_amdgcn_ballot_w64(alpha != 1.f) != 0ull) {
; #pragma unroll
;           for (int dt = 0; dt < 4; ++dt) o[dt][nt] *= alpha;
;         }
; #pragma unroll
;         for (int kk = 0; kk < 2; ++kk) {
;           u32x2 lo = pack4(s[2 * kk][nt]), hi = pack4(s[2 * kk + 1][nt]);
;           u32x4 pk = u32x4{lo.x, lo.y, hi.x, hi.y};
;           pf[nt][kk] = __builtin_bit_cast(bf16x8, pk);
;         }
;       }
;       const char* sV = cur + 64 * 208;
; #pragma unroll
;       for (int dt = 0; dt < 4; ++dt)
; #pragma unroll
;         for (int kk = 0; kk < 2; ++kk) {
;           u32x2 lo = *(const u32x2*)(sV + (dt * 16 + c16) * LDA + (kk * 32 + g * 4) * 2);
;           u32x2 hi = *(const u32x2*)(sV + (dt * 16 + c16) * LDA + (kk * 32 + 16 + g * 4) * 2);
;           u32x4 pk = u32x4{lo.x, lo.y, hi.x, hi.y};
;           bf16x8 vf = __builtin_bit_cast(bf16x8, pk);
; #pragma unroll
;           for (int nt = 0; nt < 2; ++nt) o[dt][nt] = __builtin_amdgcn_mfma_f32_16x16x32_bf16(vf, pf[nt][kk], o[dt][nt], 0, 0, 0);
;         }
.LBB0_304:
	v_sub_f32_e32 v104, v104, v2
	v_exp_f32_e32 v149, v104
	v_sub_f32_e32 v105, v105, v2
	v_exp_f32_e32 v105, v105
	v_sub_f32_e32 v106, v106, v2
	v_exp_f32_e32 v106, v106
	v_sub_f32_e32 v107, v107, v2
	v_exp_f32_e32 v107, v107
	v_sub_f32_e32 v100, v100, v2
	v_add_f32_e32 v104, 0, v149
	v_exp_f32_e32 v159, v100
	v_sub_f32_e32 v101, v101, v2
	v_add_f32_e32 v104, v105, v104
	v_exp_f32_e32 v160, v101
	v_sub_f32_e32 v101, v102, v2
	v_add_f32_e32 v104, v106, v104
	v_exp_f32_e32 v161, v101
	v_sub_f32_e32 v101, v103, v2
	v_add_f32_e32 v104, v107, v104
	v_exp_f32_e32 v103, v101
	v_sub_f32_e32 v96, v96, v2
	v_add_f32_e32 v100, v159, v104
	v_exp_f32_e32 v96, v96
	v_sub_f32_e32 v97, v97, v2
	v_add_f32_e32 v100, v160, v100
	v_exp_f32_e32 v97, v97
	v_sub_f32_e32 v98, v98, v2
	v_add_f32_e32 v100, v161, v100
	v_exp_f32_e32 v98, v98
	v_sub_f32_e32 v99, v99, v2
	v_add_f32_e32 v100, v103, v100
	v_exp_f32_e32 v99, v99
	v_sub_f32_e32 v101, v108, v2
	v_add_f32_e32 v100, v96, v100
	v_exp_f32_e32 v108, v101
	v_sub_f32_e32 v101, v109, v2
	v_add_f32_e32 v100, v97, v100
	v_exp_f32_e32 v109, v101
	v_sub_f32_e32 v101, v110, v2
	v_add_f32_e32 v100, v98, v100
	v_exp_f32_e32 v110, v101
	v_sub_f32_e32 v101, v111, v2
	v_sub_f32_e32 v88, v88, v3
	v_add_f32_e32 v100, v99, v100
	v_exp_f32_e32 v111, v101
	v_exp_f32_e32 v88, v88
	v_sub_f32_e32 v89, v89, v3
	v_add_f32_e32 v100, v108, v100
	v_exp_f32_e32 v89, v89
	v_sub_f32_e32 v90, v90, v3
	v_add_f32_e32 v100, v109, v100
	v_exp_f32_e32 v90, v90
	v_sub_f32_e32 v91, v91, v3
	v_add_f32_e32 v100, v110, v100
	v_exp_f32_e32 v91, v91
	v_sub_f32_e32 v84, v84, v3
	v_add_f32_e32 v104, v111, v100
	v_cvt_pk_bf16_f32 v100, v149, v105
	v_cvt_pk_bf16_f32 v101, v106, v107
	v_add_f32_e32 v105, 0, v88
	v_exp_f32_e32 v106, v84
	v_sub_f32_e32 v85, v85, v3
	v_add_f32_e32 v105, v89, v105
	v_exp_f32_e32 v107, v85
	v_sub_f32_e32 v85, v86, v3
	v_cvt_pk_bf16_f32 v96, v96, v97
	v_cvt_pk_bf16_f32 v97, v98, v99
	v_cvt_pk_bf16_f32 v98, v108, v109
	v_add_f32_e32 v105, v90, v105
	v_exp_f32_e32 v108, v85
	v_sub_f32_e32 v85, v87, v3
	v_add_f32_e32 v105, v91, v105
	v_exp_f32_e32 v87, v85
	v_sub_f32_e32 v80, v80, v3
	v_add_f32_e32 v84, v106, v105
	v_exp_f32_e32 v80, v80
	v_sub_f32_e32 v81, v81, v3
	v_add_f32_e32 v84, v107, v84
	v_exp_f32_e32 v81, v81
	v_sub_f32_e32 v82, v82, v3
	v_add_f32_e32 v84, v108, v84
	v_exp_f32_e32 v82, v82
	v_sub_f32_e32 v83, v83, v3
	v_add_f32_e32 v84, v87, v84
	v_exp_f32_e32 v83, v83
	v_sub_f32_e32 v85, v92, v3
	v_add_f32_e32 v84, v80, v84
	v_exp_f32_e32 v92, v85
	v_sub_f32_e32 v85, v93, v3
	v_add_f32_e32 v84, v81, v84
	v_exp_f32_e32 v93, v85
	v_sub_f32_e32 v85, v94, v3
	v_add_f32_e32 v84, v82, v84
	v_exp_f32_e32 v94, v85
	v_sub_f32_e32 v85, v95, v3
	v_add_f32_e32 v84, v83, v84
	v_exp_f32_e32 v95, v85
	v_add_f32_e32 v84, v92, v84
	v_add_f32_e32 v84, v93, v84
	v_add_f32_e32 v84, v94, v84
	v_add_f32_e32 v105, v95, v84
	v_fmac_f32_e32 v105, v147, v0
	v_cvt_pk_bf16_f32 v84, v88, v89
	v_cvt_pk_bf16_f32 v85, v90, v91
	v_cvt_pk_bf16_f32 v102, v159, v160
	v_cvt_pk_bf16_f32 v103, v161, v103
	v_cvt_pk_bf16_f32 v86, v106, v107
	v_cvt_pk_bf16_f32 v87, v108, v87
	v_cvt_pk_bf16_f32 v99, v110, v111
	v_cvt_pk_bf16_f32 v80, v80, v81
	v_cvt_pk_bf16_f32 v81, v82, v83
	v_cvt_pk_bf16_f32 v82, v92, v93
	v_cvt_pk_bf16_f32 v83, v94, v95
	v_fmac_f32_e32 v104, v146, v148
	v_mov_b64_e32 v[146:147], v[104:105]
	v_mov_b64_e32 v[148:149], v[2:3]
	s_waitcnt lgkmcnt(0)
	v_mfma_f32_16x16x32_bf16 v[76:79], v[210:213], v[100:103], v[76:79]
	v_mfma_f32_16x16x32_bf16 v[52:55], v[210:213], v[84:87], v[52:55]
	v_mfma_f32_16x16x32_bf16 v[72:75], v[218:221], v[100:103], v[72:75]
	v_mfma_f32_16x16x32_bf16 v[44:47], v[218:221], v[84:87], v[44:47]
	v_mfma_f32_16x16x32_bf16 v[68:71], v[226:229], v[100:103], v[68:71]
	v_mfma_f32_16x16x32_bf16 v[32:35], v[226:229], v[84:87], v[32:35]
	v_mfma_f32_16x16x32_bf16 v[64:67], v[234:237], v[100:103], v[64:67]
	v_mfma_f32_16x16x32_bf16 v[36:39], v[234:237], v[84:87], v[36:39]
	v_mfma_f32_16x16x32_bf16 v[76:79], v[214:217], v[96:99], v[76:79]
	v_mfma_f32_16x16x32_bf16 v[52:55], v[214:217], v[80:83], v[52:55]
	v_mfma_f32_16x16x32_bf16 v[72:75], v[222:225], v[96:99], v[72:75]
	v_mfma_f32_16x16x32_bf16 v[44:47], v[222:225], v[80:83], v[44:47]
	v_mfma_f32_16x16x32_bf16 v[68:71], v[230:233], v[96:99], v[68:71]
	v_mfma_f32_16x16x32_bf16 v[32:35], v[230:233], v[80:83], v[32:35]
	v_mfma_f32_16x16x32_bf16 v[64:67], v[238:241], v[96:99], v[64:67]
	v_mfma_f32_16x16x32_bf16 v[36:39], v[238:241], v[80:83], v[36:39]

; DI void attn_item(const int tid_, const Params& p, int l, int item, char* s0, char* s1, char* s2) {
;     ...
;     if (kt < vis) {
;       int key0, nvalid;
;       tile_info(kt, key0, nvalid);
;       f32x4 s[4][2];
; #pragma unroll
;       for (int mt = 0; mt < 4; ++mt)
; #pragma unroll
;         for (int nt = 0; nt < 2; ++nt) s[mt][nt] = f32x4{0, 0, 0, 0};
; #pragma unroll
;       for (int ks = 0; ks < 3; ++ks)
; #pragma unroll
;         for (int mt = 0; mt < 4; ++mt) {
;           bf16x8 kf = *(const bf16x8*)(cur + (mt * 16 + c16) * 208 + ks * 64 + g * 16);
; #pragma unroll
;           for (int nt = 0; nt < 2; ++nt) s[mt][nt] = __builtin_amdgcn_mfma_f32_16x16x32_bf16(kf, qf[nt][ks], s[mt][nt], 0, 0, 0);
;         }
;       if (nvalid < 64) {
; #pragma unroll
;         for (int mt = 0; mt < 4; ++mt)
; #pragma unroll
;           for (int nt = 0; nt < 2; ++nt)
; #pragma unroll
;             for (int e = 0; e < 4; ++e)
;               if (mt * 16 + g * 4 + e >= nvalid) s[mt][nt][e] = -1e30f;
;       }
;     ...
;       const char* sV = cur + 64 * 208;
; #pragma unroll
;       for (int dt = 0; dt < 4; ++dt)
; #pragma unroll
;         for (int kk = 0; kk < 2; ++kk) {
;           u32x2 lo = *(const u32x2*)(sV + (dt * 16 + c16) * LDA + (kk * 32 + g * 4) * 2);
;           u32x2 hi = *(const u32x2*)(sV + (dt * 16 + c16) * LDA + (kk * 32 + 16 + g * 4) * 2);
.LBB0_319:
	v_cmp_lt_u32_e32 vcc, s28, v150
	s_and_saveexec_b64 s[14:15], vcc
	s_cbranch_execz .LBB0_305
	s_and_b64 s[8:9], s[30:31], exec
	s_cselect_b32 s28, 0, 0x6000
	v_or_b32_e32 v0, s28, v114
	v_add_u32_e32 v0, v0, v135
	s_waitcnt lgkmcnt(0)
	ds_read_b128 v[210:213], v0
	ds_read_b128 v[214:217], v0 offset:3328
	ds_read_b128 v[218:221], v0 offset:6656
	ds_read_b128 v[222:225], v0 offset:9984
	ds_read_b128 v[226:229], v0 offset:64
	ds_read_b128 v[230:233], v0 offset:3392
	ds_read_b128 v[234:237], v0 offset:6720
	ds_read_b128 v[238:241], v0 offset:10048
	ds_read_b128 v[242:245], v0 offset:128
	ds_read_b128 v[246:249], v0 offset:3456
	ds_read_b128 v[160:163], v0 offset:6784
	ds_read_b128 v[172:175], v0 offset:10112
	s_cmp_lg_u32 s48, 34
	s_cselect_b64 s[8:9], -1, 0
	s_xor_b64 s[50:51], s[2:3], -1
	s_or_b64 s[8:9], s[50:51], s[8:9]
	s_waitcnt lgkmcnt(8)
	v_mfma_f32_16x16x32_bf16 v[104:107], v[210:213], v[4:7], 0
	v_mfma_f32_16x16x32_bf16 v[88:91], v[210:213], v[16:19], 0
	v_mfma_f32_16x16x32_bf16 v[100:103], v[214:217], v[4:7], 0
	v_mfma_f32_16x16x32_bf16 v[84:87], v[214:217], v[16:19], 0
	v_mfma_f32_16x16x32_bf16 v[96:99], v[218:221], v[4:7], 0
	v_mfma_f32_16x16x32_bf16 v[80:83], v[218:221], v[16:19], 0
	v_mfma_f32_16x16x32_bf16 v[108:111], v[222:225], v[4:7], 0
	v_mfma_f32_16x16x32_bf16 v[92:95], v[222:225], v[16:19], 0
	s_waitcnt lgkmcnt(4)
	v_mfma_f32_16x16x32_bf16 v[104:107], v[226:229], v[8:11], v[104:107]
	v_mfma_f32_16x16x32_bf16 v[88:91], v[226:229], v[20:23], v[88:91]
	v_mfma_f32_16x16x32_bf16 v[100:103], v[230:233], v[8:11], v[100:103]
	v_mfma_f32_16x16x32_bf16 v[84:87], v[230:233], v[20:23], v[84:87]
	v_mfma_f32_16x16x32_bf16 v[96:99], v[234:237], v[8:11], v[96:99]
	v_mfma_f32_16x16x32_bf16 v[80:83], v[234:237], v[20:23], v[80:83]
	v_mfma_f32_16x16x32_bf16 v[108:111], v[238:241], v[8:11], v[108:111]
	v_mfma_f32_16x16x32_bf16 v[92:95], v[238:241], v[20:23], v[92:95]
	s_waitcnt lgkmcnt(0)
	v_mfma_f32_16x16x32_bf16 v[104:107], v[242:245], v[12:15], v[104:107]
	v_mfma_f32_16x16x32_bf16 v[88:91], v[242:245], v[24:27], v[88:91]
	v_mfma_f32_16x16x32_bf16 v[100:103], v[246:249], v[12:15], v[100:103]
	v_mfma_f32_16x16x32_bf16 v[84:87], v[246:249], v[24:27], v[84:87]
	v_mfma_f32_16x16x32_bf16 v[96:99], v[160:163], v[12:15], v[96:99]
	v_mfma_f32_16x16x32_bf16 v[80:83], v[160:163], v[24:27], v[80:83]
	v_mfma_f32_16x16x32_bf16 v[108:111], v[172:175], v[12:15], v[108:111]
	v_mfma_f32_16x16x32_bf16 v[92:95], v[172:175], v[24:27], v[92:95]
	s_and_b64 vcc, exec, s[8:9]
	s_and_b64 s[50:51], s[30:31], exec
	s_mov_b32 s50, 0x9400
	s_cselect_b32 s50, 0x3400, s50
	v_or_b32_e32 v186, s50, v157
	v_add_u32_e32 v186, v186, v158
	v_add_u32_e32 v187, 0x800, v186
	v_add_u32_e32 v188, 0x1000, v186
	v_add_u32_e32 v189, 0x1800, v186
	ds_read2_b64 v[210:213], v186 offset1:4
	ds_read2_b64 v[214:217], v186 offset0:8 offset1:12
	ds_read2_b64 v[218:221], v187 offset0:32 offset1:36
	ds_read2_b64 v[222:225], v187 offset0:40 offset1:44
	ds_read2_b64 v[226:229], v188 offset0:64 offset1:68
	ds_read2_b64 v[230:233], v188 offset0:72 offset1:76
	ds_read2_b64 v[234:237], v189 offset0:96 offset1:100
	ds_read2_b64 v[238:241], v189 offset0:104 offset1:108
	s_cbranch_vccnz .LBB0_322
	s_nop 6
	v_mov_b32_e32 v92, 0xf149f2ca
	v_mov_b32_e32 v93, v92
	v_mov_b32_e32 v94, v92
	v_mov_b32_e32 v95, v92
	v_mov_b32_e32 v108, v92
	v_mov_b32_e32 v109, v92
	v_mov_b32_e32 v110, v92
	v_mov_b32_e32 v111, v92
	v_mov_b32_e32 v80, v92
	v_mov_b32_e32 v81, v92
	v_mov_b32_e32 v82, v92
	v_mov_b32_e32 v83, v92
	v_mov_b32_e32 v96, v92
	v_mov_b32_e32 v97, v92
	v_mov_b32_e32 v98, v92
	v_mov_b32_e32 v99, v92
	v_mov_b32_e32 v84, v92
	v_mov_b32_e32 v85, v92
	v_mov_b32_e32 v86, v92
	v_mov_b32_e32 v87, v92
	v_mov_b32_e32 v100, v92
	v_mov_b32_e32 v101, v92
	v_mov_b32_e32 v102, v92
	v_mov_b32_e32 v103, v92
